# spatial gMLP phase: v tile, row-rms, gain/bias, W and u loads all issued before the first wait (counted vmcnt for the tile), epilogue gain/bias from registers: one load latency per task instead of thr
# baseline (speedup 1.0000x reference)
.LBB0_215:
	v_add_u32_e32 v0, s13, v72
	v_ashrrev_i32_e32 v1, 31, v0
	v_lshlrev_b64 v[0:1], 8, v[0:1]
	v_lshl_add_u64 v[4:5], v[62:63], 0, v[0:1]
	global_load_dwordx4 v[0:3], v[4:5], off
	global_load_dwordx4 v[56:59], v[4:5], off offset:32
	global_load_dwordx4 v[52:55], v[4:5], off offset:64
	global_load_dwordx4 v[48:51], v[4:5], off offset:96
	global_load_dwordx4 v[44:47], v[4:5], off offset:128
	global_load_dwordx4 v[40:43], v[4:5], off offset:160
	global_load_dwordx4 v[36:39], v[4:5], off offset:192
	global_load_dwordx4 v[32:35], v[4:5], off offset:224
	v_add_u32_e32 v4, s12, v73
	v_or_b32_e32 v110, 25, v4
	v_ashrrev_i32_e32 v111, 31, v110
	v_lshl_add_u64 v[6:7], v[64:65], 0, s[96:97]
	v_ashrrev_i32_e32 v5, 31, v4
	v_lshlrev_b64 v[110:111], 11, v[110:111]
	v_lshlrev_b64 v[68:69], 11, v[4:5]
	v_or_b32_e32 v10, 1, v4
	v_or_b32_e32 v12, 2, v4
	v_or_b32_e32 v14, 3, v4
	v_or_b32_e32 v16, 8, v4
	v_or_b32_e32 v18, 9, v4
	v_or_b32_e32 v20, 10, v4
	v_or_b32_e32 v22, 11, v4
	v_or_b32_e32 v24, 16, v4
	v_or_b32_e32 v26, 17, v4
	v_or_b32_e32 v28, 18, v4
	v_or_b32_e32 v30, 19, v4
	v_or_b32_e32 v108, 24, v4
	v_lshl_add_u64 v[140:141], v[6:7], 0, v[110:111]
	v_or_b32_e32 v110, 26, v4
	v_or_b32_e32 v4, 27, v4
	v_ashrrev_i32_e32 v11, 31, v10
	v_ashrrev_i32_e32 v109, 31, v108
	v_ashrrev_i32_e32 v5, 31, v4
	v_lshlrev_b64 v[10:11], 11, v[10:11]
	v_ashrrev_i32_e32 v13, 31, v12
	v_ashrrev_i32_e32 v15, 31, v14
	v_ashrrev_i32_e32 v17, 31, v16
	v_ashrrev_i32_e32 v19, 31, v18
	v_ashrrev_i32_e32 v21, 31, v20
	v_ashrrev_i32_e32 v23, 31, v22
	v_ashrrev_i32_e32 v25, 31, v24
	v_ashrrev_i32_e32 v27, 31, v26
	v_ashrrev_i32_e32 v29, 31, v28
	v_ashrrev_i32_e32 v31, 31, v30
	v_lshlrev_b64 v[108:109], 11, v[108:109]
	v_ashrrev_i32_e32 v111, 31, v110
	v_lshlrev_b64 v[4:5], 11, v[4:5]
	v_lshl_add_u64 v[8:9], v[6:7], 0, v[68:69]
	v_lshl_add_u64 v[10:11], v[6:7], 0, v[10:11]
	v_lshlrev_b64 v[12:13], 11, v[12:13]
	v_lshlrev_b64 v[14:15], 11, v[14:15]
	v_lshlrev_b64 v[16:17], 11, v[16:17]
	v_lshlrev_b64 v[18:19], 11, v[18:19]
	v_lshlrev_b64 v[20:21], 11, v[20:21]
	v_lshlrev_b64 v[22:23], 11, v[22:23]
	v_lshlrev_b64 v[24:25], 11, v[24:25]
	v_lshlrev_b64 v[26:27], 11, v[26:27]
	v_lshlrev_b64 v[28:29], 11, v[28:29]
	v_lshlrev_b64 v[30:31], 11, v[30:31]
	v_lshl_add_u64 v[108:109], v[6:7], 0, v[108:109]
	v_lshlrev_b64 v[110:111], 11, v[110:111]
	v_lshl_add_u64 v[4:5], v[6:7], 0, v[4:5]
	v_lshl_add_u64 v[12:13], v[6:7], 0, v[12:13]
	v_lshl_add_u64 v[14:15], v[6:7], 0, v[14:15]
	v_lshl_add_u64 v[16:17], v[6:7], 0, v[16:17]
	v_lshl_add_u64 v[18:19], v[6:7], 0, v[18:19]
	v_lshl_add_u64 v[20:21], v[6:7], 0, v[20:21]
	v_lshl_add_u64 v[22:23], v[6:7], 0, v[22:23]
	v_lshl_add_u64 v[24:25], v[6:7], 0, v[24:25]
	v_lshl_add_u64 v[26:27], v[6:7], 0, v[26:27]
	v_lshl_add_u64 v[28:29], v[6:7], 0, v[28:29]
	v_lshl_add_u64 v[30:31], v[6:7], 0, v[30:31]
	v_lshl_add_u64 v[142:143], v[6:7], 0, v[110:111]
	global_load_ushort v137, v[8:9], off
	global_load_ushort v138, v[8:9], off offset:64
	global_load_ushort v135, v[10:11], off
	global_load_ushort v136, v[10:11], off offset:64
	global_load_ushort v133, v[12:13], off
	global_load_ushort v134, v[12:13], off offset:64
	global_load_ushort v131, v[14:15], off
	global_load_ushort v132, v[14:15], off offset:64
	global_load_ushort v129, v[16:17], off
	global_load_ushort v130, v[16:17], off offset:64
	global_load_ushort v127, v[18:19], off
	global_load_ushort v128, v[18:19], off offset:64
	global_load_ushort v125, v[20:21], off
	global_load_ushort v126, v[20:21], off offset:64
	global_load_ushort v123, v[22:23], off
	global_load_ushort v124, v[22:23], off offset:64
	global_load_ushort v121, v[24:25], off
	global_load_ushort v122, v[24:25], off offset:64
	global_load_ushort v119, v[26:27], off
	global_load_ushort v120, v[26:27], off offset:64
	global_load_ushort v117, v[28:29], off
	global_load_ushort v118, v[28:29], off offset:64
	global_load_ushort v115, v[30:31], off
	global_load_ushort v116, v[30:31], off offset:64
	global_load_ushort v113, v[108:109], off
	global_load_ushort v114, v[108:109], off offset:64
	global_load_ushort v111, v[140:141], off
	global_load_ushort v112, v[140:141], off offset:64
	s_nop 0
	global_load_ushort v109, v[142:143], off
	global_load_ushort v110, v[142:143], off offset:64
	global_load_ushort v107, v[4:5], off
	global_load_ushort v108, v[4:5], off offset:64
	s_waitcnt vmcnt(46)
	ds_write_b128 v103, v[180:183]
	ds_write_b128 v104, v[184:187]
	ds_write_b128 v105, v[188:191]
	ds_write_b128 v106, v[192:195]
	s_and_saveexec_b64 s[2:3], vcc
	s_cbranch_execz .Lsp_norss2
	v_fmamk_f32 v216, v196, 0x3a800000, v225
	v_mul_f32_e32 v217, 0x4b800000, v216
	v_cmp_gt_f32_e64 s[100:101], s93, v216
	s_nop 1
	v_cndmask_b32_e64 v216, v216, v217, s[100:101]
	v_rsq_f32_e32 v216, v216
	s_nop 0
	v_mul_f32_e32 v217, 0x45800000, v216
	v_cndmask_b32_e64 v216, v216, v217, s[100:101]
	ds_write_b32 v71, v216 offset:34816
.Lsp_norss2:
	s_or_b64 exec, exec, s[2:3]
	s_waitcnt lgkmcnt(0)
	s_barrier
	ds_read_b128 v[4:7], v79 offset:34816
	ds_read_b128 v[8:11], v79 offset:34832
	v_readlane_b32 s0, v254, 29
	s_add_i32 s6, s6, s7
	s_waitcnt vmcnt(39)
	v_lshlrev_b32_e32 v12, 16, v0
	v_and_b32_e32 v13, 0xffff0000, v0
	v_lshlrev_b32_e32 v0, 16, v1
	v_and_b32_e32 v1, 0xffff0000, v1
	s_waitcnt lgkmcnt(1)
	v_pk_mul_f32 v[6:7], v[6:7], v[0:1]
	v_lshlrev_b32_e32 v0, 16, v2
	v_and_b32_e32 v1, 0xffff0000, v2
	s_waitcnt lgkmcnt(0)
	v_pk_mul_f32 v[8:9], v[8:9], v[0:1]
	v_lshlrev_b32_e32 v0, 16, v3
	v_and_b32_e32 v1, 0xffff0000, v3
	v_pk_mul_f32 v[4:5], v[4:5], v[12:13]
	v_pk_mul_f32 v[10:11], v[10:11], v[0:1]
	v_cvt_pk_bf16_f32 v0, v4, v5
	v_cvt_pk_bf16_f32 v1, v6, v7
	v_cvt_pk_bf16_f32 v2, v8, v9
	v_cvt_pk_bf16_f32 v3, v10, v11
	ds_read_u16 v4, v80
	ds_read_u16 v8, v80 offset:64
	ds_read_u16 v9, v80 offset:272
	ds_read_u16 v10, v80 offset:336
	ds_read_u16 v5, v80 offset:544
	ds_read_u16 v11, v80 offset:608
	ds_read_u16 v12, v80 offset:816
	ds_read_u16 v13, v80 offset:880
	ds_read_u16 v6, v80 offset:1088
	ds_read_u16 v14, v80 offset:1152
	ds_read_u16 v15, v80 offset:1360
	ds_read_u16 v139, v80 offset:1424
	ds_read_u16 v7, v80 offset:1632
	ds_read_u16 v140, v80 offset:1696
	ds_read_u16 v16, v80 offset:1904
	ds_read_u16 v141, v80 offset:1968
	s_waitcnt lgkmcnt(5)
	v_perm_b32 v6, v15, v6, s48
	v_perm_b32 v5, v12, v5, s48
	v_perm_b32 v4, v9, v4, s48
	s_waitcnt lgkmcnt(1)
	v_perm_b32 v7, v16, v7, s48
	s_waitcnt vmcnt(38)
	v_lshlrev_b32_e32 v148, 16, v56
	v_and_b32_e32 v149, 0xffff0000, v56
	v_mfma_f32_32x32x16_bf16 v[16:31], v[0:3], v[4:7], 0
	s_waitcnt lgkmcnt(0)
	v_perm_b32 v7, v141, v140, s48
	ds_read_b128 v[140:143], v79 offset:34880
	ds_read_b128 v[144:147], v79 offset:34896
	v_lshlrev_b32_e32 v56, 16, v57
	v_and_b32_e32 v57, 0xffff0000, v57
	v_perm_b32 v6, v139, v14, s48
	v_perm_b32 v5, v13, v11, s48
	v_perm_b32 v4, v10, v8, s48
	s_waitcnt lgkmcnt(1)
	v_pk_mul_f32 v[142:143], v[142:143], v[56:57]
	v_lshlrev_b32_e32 v56, 16, v58
	v_and_b32_e32 v57, 0xffff0000, v58
	v_mfma_f32_32x32x16_bf16 v[0:15], v[0:3], v[4:7], 0
	s_waitcnt lgkmcnt(0)
	v_mul_f32_e64 v144, v144, v56
	v_mul_f32_e64 v145, v145, v57
	v_lshlrev_b32_e32 v56, 16, v59
	v_and_b32_e32 v57, 0xffff0000, v59
	v_pk_mul_f32 v[140:141], v[140:141], v[148:149]
	v_pk_mul_f32 v[146:147], v[146:147], v[56:57]
	v_cvt_pk_bf16_f32 v56, v140, v141
	v_cvt_pk_bf16_f32 v57, v142, v143
	v_cvt_pk_bf16_f32 v58, v144, v145
	v_cvt_pk_bf16_f32 v59, v146, v147
	ds_read_u16 v139, v81
	ds_read_u16 v144, v81 offset:64
	ds_read_u16 v140, v80 offset:4624
	ds_read_u16 v145, v80 offset:4688
	ds_read_u16 v141, v80 offset:4896
	ds_read_u16 v146, v80 offset:4960
	ds_read_u16 v147, v80 offset:5168
	ds_read_u16 v148, v80 offset:5232
	ds_read_u16 v142, v80 offset:5440
	ds_read_u16 v149, v80 offset:5504
	ds_read_u16 v150, v80 offset:5712
	ds_read_u16 v151, v80 offset:5776
	ds_read_u16 v143, v80 offset:5984
	ds_read_u16 v152, v80 offset:6048
	ds_read_u16 v153, v80 offset:6256
	ds_read_u16 v154, v80 offset:6320
	s_waitcnt lgkmcnt(5)
	v_perm_b32 v142, v150, v142, s48
	v_perm_b32 v141, v147, v141, s48
	v_perm_b32 v140, v140, v139, s48
	s_waitcnt lgkmcnt(1)
	v_perm_b32 v143, v153, v143, s48
	s_add_i32 s8, s8, s9
	s_add_i32 s10, s10, s11
	v_mfma_f32_32x32x16_bf16 v[16:31], v[56:59], v[140:143], v[16:31]
	s_waitcnt lgkmcnt(0)
	v_perm_b32 v143, v154, v152, s48
	v_perm_b32 v142, v151, v149, s48
	v_perm_b32 v141, v148, v146, s48
	v_perm_b32 v140, v145, v144, s48
	s_waitcnt vmcnt(37)
	v_lshlrev_b32_e32 v144, 16, v52
	v_and_b32_e32 v145, 0xffff0000, v52
	v_lshlrev_b32_e32 v52, 16, v53
	v_mfma_f32_32x32x16_bf16 v[0:15], v[56:59], v[140:143], v[0:15]
	ds_read_b128 v[56:59], v79 offset:34944
	ds_read_b128 v[140:143], v79 offset:34960
	v_and_b32_e32 v53, 0xffff0000, v53
	s_cmpk_lt_i32 s6, 0x300
	s_waitcnt lgkmcnt(1)
	v_pk_mul_f32 v[58:59], v[58:59], v[52:53]
	v_lshlrev_b32_e32 v52, 16, v54
	v_and_b32_e32 v53, 0xffff0000, v54
	s_waitcnt lgkmcnt(0)
	v_pk_mul_f32 v[140:141], v[140:141], v[52:53]
	v_lshlrev_b32_e32 v52, 16, v55
	v_and_b32_e32 v53, 0xffff0000, v55
	v_pk_mul_f32 v[56:57], v[56:57], v[144:145]
	v_pk_mul_f32 v[142:143], v[142:143], v[52:53]
	v_cvt_pk_bf16_f32 v52, v56, v57
	v_cvt_pk_bf16_f32 v53, v58, v59
	v_cvt_pk_bf16_f32 v54, v140, v141
	v_cvt_pk_bf16_f32 v55, v142, v143
	ds_read_u16 v56, v82
	ds_read_u16 v139, v82 offset:64
	ds_read_u16 v140, v80 offset:8976
	ds_read_u16 v141, v80 offset:9040
	ds_read_u16 v57, v80 offset:9248
	ds_read_u16 v142, v80 offset:9312
	ds_read_u16 v143, v80 offset:9520
	ds_read_u16 v144, v80 offset:9584
	ds_read_u16 v58, v80 offset:9792
	ds_read_u16 v145, v80 offset:9856
	ds_read_u16 v146, v80 offset:10064
	ds_read_u16 v147, v80 offset:10128
	ds_read_u16 v59, v80 offset:10336
	ds_read_u16 v148, v80 offset:10400
	ds_read_u16 v149, v80 offset:10608
	ds_read_u16 v150, v80 offset:10672
	s_waitcnt lgkmcnt(5)
	v_perm_b32 v58, v146, v58, s48
	v_perm_b32 v57, v143, v57, s48
	v_perm_b32 v56, v140, v56, s48
	s_waitcnt lgkmcnt(1)
	v_perm_b32 v59, v149, v59, s48
	s_waitcnt vmcnt(36)
	v_lshlrev_b32_e32 v140, 16, v48
	v_mfma_f32_32x32x16_bf16 v[16:31], v[52:55], v[56:59], v[16:31]
	s_waitcnt lgkmcnt(0)
	v_perm_b32 v59, v150, v148, s48
	v_perm_b32 v58, v147, v145, s48
	v_perm_b32 v57, v144, v142, s48
	v_perm_b32 v56, v141, v139, s48
	v_and_b32_e32 v141, 0xffff0000, v48
	v_lshlrev_b32_e32 v48, 16, v49
	v_and_b32_e32 v49, 0xffff0000, v49
	v_mfma_f32_32x32x16_bf16 v[0:15], v[52:55], v[56:59], v[0:15]
	ds_read_b128 v[52:55], v79 offset:35008
	ds_read_b128 v[56:59], v79 offset:35024
	s_waitcnt lgkmcnt(1)
	v_mul_f32_e64 v54, v54, v48
	v_mul_f32_e64 v55, v55, v49
	v_lshlrev_b32_e32 v48, 16, v50
	v_and_b32_e32 v49, 0xffff0000, v50
	s_waitcnt lgkmcnt(0)
	v_pk_mul_f32 v[56:57], v[56:57], v[48:49]
	v_lshlrev_b32_e32 v48, 16, v51
	v_and_b32_e32 v49, 0xffff0000, v51
	v_pk_mul_f32 v[52:53], v[52:53], v[140:141]
	v_pk_mul_f32 v[58:59], v[58:59], v[48:49]
	v_cvt_pk_bf16_f32 v48, v52, v53
	v_cvt_pk_bf16_f32 v49, v54, v55
	v_cvt_pk_bf16_f32 v50, v56, v57
	v_cvt_pk_bf16_f32 v51, v58, v59
	ds_read_u16 v52, v83
	ds_read_u16 v56, v83 offset:64
	ds_read_u16 v57, v80 offset:13328
	ds_read_u16 v58, v80 offset:13392
	ds_read_u16 v53, v80 offset:13600
	ds_read_u16 v59, v80 offset:13664
	ds_read_u16 v139, v80 offset:13872
	ds_read_u16 v140, v80 offset:13936
	ds_read_u16 v54, v80 offset:14144
	ds_read_u16 v141, v80 offset:14208
	ds_read_u16 v142, v80 offset:14416
	ds_read_u16 v143, v80 offset:14480
	ds_read_u16 v55, v80 offset:14688
	ds_read_u16 v144, v80 offset:14752
	ds_read_u16 v145, v80 offset:14960
	ds_read_u16 v146, v80 offset:15024
	s_waitcnt lgkmcnt(5)
	v_perm_b32 v54, v142, v54, s48
	v_perm_b32 v53, v139, v53, s48
	v_perm_b32 v52, v57, v52, s48
	s_waitcnt lgkmcnt(1)
	v_perm_b32 v55, v145, v55, s48
	s_waitcnt vmcnt(35)
	v_and_b32_e32 v57, 0xffff0000, v44
	v_mfma_f32_32x32x16_bf16 v[16:31], v[48:51], v[52:55], v[16:31]
	s_waitcnt lgkmcnt(0)
	v_perm_b32 v55, v146, v144, s48
	v_perm_b32 v54, v143, v141, s48
	v_perm_b32 v53, v140, v59, s48
	v_perm_b32 v52, v58, v56, s48
	v_lshlrev_b32_e32 v56, 16, v44
	v_lshlrev_b32_e32 v44, 16, v45
	v_and_b32_e32 v45, 0xffff0000, v45
	v_mfma_f32_32x32x16_bf16 v[0:15], v[48:51], v[52:55], v[0:15]
	ds_read_b128 v[48:51], v79 offset:35072
	ds_read_b128 v[52:55], v79 offset:35088
	s_waitcnt lgkmcnt(1)
	v_mul_f32_e64 v50, v50, v44
	v_mul_f32_e64 v51, v51, v45
	v_lshlrev_b32_e32 v44, 16, v46
	v_and_b32_e32 v45, 0xffff0000, v46
	s_waitcnt lgkmcnt(0)
	v_pk_mul_f32 v[52:53], v[52:53], v[44:45]
	v_lshlrev_b32_e32 v44, 16, v47
	v_and_b32_e32 v45, 0xffff0000, v47
	v_pk_mul_f32 v[48:49], v[48:49], v[56:57]
	v_pk_mul_f32 v[54:55], v[54:55], v[44:45]
	v_cvt_pk_bf16_f32 v44, v48, v49
	v_cvt_pk_bf16_f32 v45, v50, v51
	v_cvt_pk_bf16_f32 v46, v52, v53
	v_cvt_pk_bf16_f32 v47, v54, v55
	ds_read_u16 v48, v84
	ds_read_u16 v52, v84 offset:64
	ds_read_u16 v53, v80 offset:17680
	ds_read_u16 v54, v80 offset:17744
	ds_read_u16 v49, v80 offset:17952
	ds_read_u16 v55, v80 offset:18016
	ds_read_u16 v56, v80 offset:18224
	ds_read_u16 v57, v80 offset:18288
	ds_read_u16 v50, v80 offset:18496
	ds_read_u16 v58, v80 offset:18560
	ds_read_u16 v59, v80 offset:18768
	ds_read_u16 v139, v80 offset:18832
	ds_read_u16 v51, v80 offset:19040
	ds_read_u16 v140, v80 offset:19104
	ds_read_u16 v141, v80 offset:19312
	ds_read_u16 v142, v80 offset:19376
	s_waitcnt lgkmcnt(5)
	v_perm_b32 v50, v59, v50, s48
	v_perm_b32 v49, v56, v49, s48
	v_perm_b32 v48, v53, v48, s48
	s_waitcnt lgkmcnt(1)
	v_perm_b32 v51, v141, v51, s48
	s_waitcnt vmcnt(34)
	v_and_b32_e32 v53, 0xffff0000, v40
	v_mfma_f32_32x32x16_bf16 v[16:31], v[44:47], v[48:51], v[16:31]
	s_waitcnt lgkmcnt(0)
	v_perm_b32 v51, v142, v140, s48
	v_perm_b32 v50, v139, v58, s48
	v_perm_b32 v49, v57, v55, s48
	v_perm_b32 v48, v54, v52, s48
	v_lshlrev_b32_e32 v52, 16, v40
	v_lshlrev_b32_e32 v40, 16, v41
	v_and_b32_e32 v41, 0xffff0000, v41
	v_mfma_f32_32x32x16_bf16 v[0:15], v[44:47], v[48:51], v[0:15]
	ds_read_b128 v[44:47], v79 offset:35136
	ds_read_b128 v[48:51], v79 offset:35152
	s_waitcnt lgkmcnt(1)
	v_mul_f32_e64 v46, v46, v40
	v_mul_f32_e64 v47, v47, v41
	v_lshlrev_b32_e32 v40, 16, v42
	v_and_b32_e32 v41, 0xffff0000, v42
	s_waitcnt lgkmcnt(0)
	v_pk_mul_f32 v[48:49], v[48:49], v[40:41]
	v_lshlrev_b32_e32 v40, 16, v43
	v_and_b32_e32 v41, 0xffff0000, v43
	v_pk_mul_f32 v[44:45], v[44:45], v[52:53]
	v_pk_mul_f32 v[50:51], v[50:51], v[40:41]
	v_cvt_pk_bf16_f32 v40, v44, v45
	v_cvt_pk_bf16_f32 v41, v46, v47
	v_cvt_pk_bf16_f32 v42, v48, v49
	v_cvt_pk_bf16_f32 v43, v50, v51
	ds_read_u16 v44, v85
	ds_read_u16 v48, v85 offset:64
	ds_read_u16 v49, v80 offset:22032
	ds_read_u16 v50, v80 offset:22096
	ds_read_u16 v45, v80 offset:22304
	ds_read_u16 v51, v80 offset:22368
	ds_read_u16 v52, v80 offset:22576
	ds_read_u16 v53, v80 offset:22640
	ds_read_u16 v46, v80 offset:22848
	ds_read_u16 v54, v80 offset:22912
	ds_read_u16 v55, v80 offset:23120
	ds_read_u16 v56, v80 offset:23184
	ds_read_u16 v47, v80 offset:23392
	ds_read_u16 v57, v80 offset:23456
	ds_read_u16 v58, v80 offset:23664
	ds_read_u16 v59, v80 offset:23728
	s_waitcnt lgkmcnt(5)
	v_perm_b32 v46, v55, v46, s48
	v_perm_b32 v45, v52, v45, s48
	v_perm_b32 v44, v49, v44, s48
	s_waitcnt lgkmcnt(1)
	v_perm_b32 v47, v58, v47, s48
	s_waitcnt vmcnt(33)
	v_and_b32_e32 v49, 0xffff0000, v36
	v_mfma_f32_32x32x16_bf16 v[16:31], v[40:43], v[44:47], v[16:31]
	s_waitcnt lgkmcnt(0)
	v_perm_b32 v47, v59, v57, s48
	v_perm_b32 v46, v56, v54, s48
	v_perm_b32 v45, v53, v51, s48
	v_perm_b32 v44, v50, v48, s48
	v_lshlrev_b32_e32 v48, 16, v36
	v_lshlrev_b32_e32 v36, 16, v37
	v_and_b32_e32 v37, 0xffff0000, v37
	v_mfma_f32_32x32x16_bf16 v[0:15], v[40:43], v[44:47], v[0:15]
	ds_read_b128 v[40:43], v79 offset:35200
	ds_read_b128 v[44:47], v79 offset:35216
	s_waitcnt lgkmcnt(1)
	v_mul_f32_e64 v42, v42, v36
	v_mul_f32_e64 v43, v43, v37
	v_lshlrev_b32_e32 v36, 16, v38
	v_and_b32_e32 v37, 0xffff0000, v38
	s_waitcnt lgkmcnt(0)
	v_pk_mul_f32 v[44:45], v[44:45], v[36:37]
	v_lshlrev_b32_e32 v36, 16, v39
	v_and_b32_e32 v37, 0xffff0000, v39
	v_pk_mul_f32 v[40:41], v[40:41], v[48:49]
	v_pk_mul_f32 v[46:47], v[46:47], v[36:37]
	v_cvt_pk_bf16_f32 v36, v40, v41
	v_cvt_pk_bf16_f32 v37, v42, v43
	v_cvt_pk_bf16_f32 v38, v44, v45
	v_cvt_pk_bf16_f32 v39, v46, v47
	ds_read_u16 v40, v86
	ds_read_u16 v44, v86 offset:64
	ds_read_u16 v45, v80 offset:26384
	ds_read_u16 v46, v80 offset:26448
	ds_read_u16 v41, v80 offset:26656
	ds_read_u16 v47, v80 offset:26720
	ds_read_u16 v48, v80 offset:26928
	ds_read_u16 v49, v80 offset:26992
	ds_read_u16 v42, v80 offset:27200
	ds_read_u16 v50, v80 offset:27264
	ds_read_u16 v51, v80 offset:27472
	ds_read_u16 v52, v80 offset:27536
	ds_read_u16 v43, v80 offset:27744
	ds_read_u16 v53, v80 offset:27808
	ds_read_u16 v54, v80 offset:28016
	ds_read_u16 v55, v80 offset:28080
	s_waitcnt lgkmcnt(5)
	v_perm_b32 v42, v51, v42, s48
	v_perm_b32 v41, v48, v41, s48
	v_perm_b32 v40, v45, v40, s48
	s_waitcnt lgkmcnt(1)
	v_perm_b32 v43, v54, v43, s48
	s_waitcnt vmcnt(32)
	v_and_b32_e32 v45, 0xffff0000, v32
	v_mfma_f32_32x32x16_bf16 v[16:31], v[36:39], v[40:43], v[16:31]
	s_waitcnt lgkmcnt(0)
	v_perm_b32 v43, v55, v53, s48
	v_perm_b32 v42, v52, v50, s48
	v_perm_b32 v41, v49, v47, s48
	v_perm_b32 v40, v46, v44, s48
	v_lshlrev_b32_e32 v44, 16, v32
	v_lshlrev_b32_e32 v32, 16, v33
	v_and_b32_e32 v33, 0xffff0000, v33
	v_mfma_f32_32x32x16_bf16 v[0:15], v[36:39], v[40:43], v[0:15]
	ds_read_b128 v[36:39], v79 offset:35264
	ds_read_b128 v[40:43], v79 offset:35280
	s_waitcnt lgkmcnt(1)
	v_mul_f32_e64 v38, v38, v32
	v_mul_f32_e64 v39, v39, v33
	v_lshlrev_b32_e32 v32, 16, v34
	v_and_b32_e32 v33, 0xffff0000, v34
	s_waitcnt lgkmcnt(0)
	v_pk_mul_f32 v[40:41], v[40:41], v[32:33]
	v_lshlrev_b32_e32 v32, 16, v35
	v_and_b32_e32 v33, 0xffff0000, v35
	v_pk_mul_f32 v[36:37], v[36:37], v[44:45]
	v_pk_mul_f32 v[42:43], v[42:43], v[32:33]
	v_cvt_pk_bf16_f32 v32, v36, v37
	v_cvt_pk_bf16_f32 v33, v38, v39
	v_cvt_pk_bf16_f32 v34, v40, v41
	v_cvt_pk_bf16_f32 v35, v42, v43
	ds_read_u16 v36, v87
	ds_read_u16 v40, v87 offset:64
	ds_read_u16 v41, v80 offset:30736
	ds_read_u16 v42, v80 offset:30800
	ds_read_u16 v37, v80 offset:31008
	ds_read_u16 v43, v80 offset:31072
	ds_read_u16 v44, v80 offset:31280
	ds_read_u16 v45, v80 offset:31344
	ds_read_u16 v38, v80 offset:31552
	ds_read_u16 v46, v80 offset:31616
	ds_read_u16 v47, v80 offset:31824
	ds_read_u16 v48, v80 offset:31888
	ds_read_u16 v39, v80 offset:32096
	ds_read_u16 v49, v80 offset:32160
	ds_read_u16 v50, v80 offset:32368
	ds_read_u16 v51, v80 offset:32432
	s_waitcnt lgkmcnt(5)
	v_perm_b32 v38, v47, v38, s48
	v_perm_b32 v37, v44, v37, s48
	v_perm_b32 v36, v41, v36, s48
	s_waitcnt lgkmcnt(1)
	v_perm_b32 v39, v50, v39, s48
	s_waitcnt vmcnt(30)
	v_lshlrev_b32_e32 v44, 16, v138
	v_mfma_f32_32x32x16_bf16 v[16:31], v[32:35], v[36:39], v[16:31]
	s_waitcnt lgkmcnt(0)
	v_perm_b32 v39, v51, v49, s48
	v_perm_b32 v38, v48, v46, s48
	v_perm_b32 v37, v45, v43, s48
	v_perm_b32 v36, v42, v40, s48
	v_lshlrev_b32_e32 v42, 16, v137
	s_nop 0
	v_mfma_f32_32x32x16_bf16 v[0:15], v[32:35], v[36:39], v[0:15]
	v_lshl_add_u64 v[32:33], v[66:67], 0, s[96:97]
	s_waitcnt vmcnt(0)
	v_mov_b32_e32 v37, v197
	v_mov_b32_e32 v36, v198
	v_mov_b64 v[38:39], v[200:201]
	v_mov_b64 v[40:41], v[202:203]
	v_mov_b64 v[48:49], v[204:205]
	v_mov_b64 v[50:51], v[206:207]
	v_mov_b64 v[52:53], v[208:209]
	v_mov_b64 v[54:55], v[210:211]
	v_mov_b64 v[56:57], v[212:213]
	v_mov_b64 v[58:59], v[214:215]
	s_nop 3
	v_fma_f32 v16, v16, v37, v38
	v_fma_f32 v0, v0, v36, v38
	v_mul_f32_e32 v16, v16, v42
	v_mul_f32_e32 v0, v0, v44
	v_cvt_pk_bf16_f32 v16, v16, s0
	v_lshl_add_u64 v[42:43], v[32:33], 0, v[68:69]
	v_cvt_pk_bf16_f32 v0, v0, s0
	global_store_short v[42:43], v16, off
	global_store_short v[42:43], v0, off offset:64
	v_add_u32_e32 v42, s12, v88
	v_ashrrev_i32_e32 v43, 31, v42
	v_lshlrev_b32_e32 v0, 16, v135
	v_fma_f32 v16, v17, v37, v39
	v_mul_f32_e32 v0, v16, v0
	v_lshlrev_b64 v[16:17], 11, v[42:43]
	v_cvt_pk_bf16_f32 v0, v0, s0
	v_lshl_add_u64 v[16:17], v[32:33], 0, v[16:17]
	v_lshlrev_b32_e32 v38, 16, v136
	global_store_short v[16:17], v0, off
	v_fma_f32 v0, v1, v36, v39
	v_mul_f32_e32 v0, v0, v38
	v_cvt_pk_bf16_f32 v0, v0, s0
	global_store_short v[16:17], v0, off offset:64
	v_add_u32_e32 v0, s12, v89
	v_ashrrev_i32_e32 v1, 31, v0
	v_lshlrev_b32_e32 v16, 16, v133
	v_lshlrev_b32_e32 v17, 16, v134
	v_fma_f32 v18, v18, v37, v40
	v_fma_f32 v2, v2, v36, v40
	v_mul_f32_e32 v16, v18, v16
	v_lshlrev_b64 v[0:1], 11, v[0:1]
	v_mul_f32_e32 v2, v2, v17
	v_cvt_pk_bf16_f32 v16, v16, s0
	v_lshl_add_u64 v[0:1], v[32:33], 0, v[0:1]
	v_cvt_pk_bf16_f32 v2, v2, s0
	global_store_short v[0:1], v16, off
	global_store_short v[0:1], v2, off offset:64
	v_add_u32_e32 v0, s12, v90
	v_ashrrev_i32_e32 v1, 31, v0
	v_lshlrev_b32_e32 v2, 16, v131
	v_fma_f32 v17, v19, v37, v41
	v_mul_f32_e32 v2, v17, v2
	v_lshlrev_b64 v[0:1], 11, v[0:1]
	v_lshlrev_b32_e32 v16, 16, v132
	v_cvt_pk_bf16_f32 v2, v2, s0
	v_lshl_add_u64 v[0:1], v[32:33], 0, v[0:1]
	v_fmac_f32_e32 v41, v3, v36
	global_store_short v[0:1], v2, off
	v_mul_f32_e32 v2, v41, v16
	v_cvt_pk_bf16_f32 v2, v2, s0
	global_store_short v[0:1], v2, off offset:64
	v_mov_b32_e32 v0, v48
	v_mov_b32_e32 v1, v49
	v_mov_b32_e32 v2, v50
	v_mov_b32_e32 v3, v51
	v_add_u32_e32 v16, s12, v91
	v_ashrrev_i32_e32 v17, 31, v16
	v_lshlrev_b32_e32 v18, 16, v129
	v_lshlrev_b32_e32 v19, 16, v130
	v_lshlrev_b64 v[16:17], 11, v[16:17]
	v_lshl_add_u64 v[16:17], v[32:33], 0, v[16:17]
	s_nop 0
	v_fma_f32 v20, v20, v37, v0
	v_fma_f32 v0, v4, v36, v0
	v_mul_f32_e32 v18, v20, v18
	v_mul_f32_e32 v0, v0, v19
	v_cvt_pk_bf16_f32 v18, v18, s0
	v_cvt_pk_bf16_f32 v0, v0, s0
	global_store_short v[16:17], v18, off
	global_store_short v[16:17], v0, off offset:64
	v_add_u32_e32 v16, s12, v92
	v_ashrrev_i32_e32 v17, 31, v16
	v_lshlrev_b32_e32 v0, 16, v127
	v_fma_f32 v18, v21, v37, v1
	v_mul_f32_e32 v0, v18, v0
	v_lshlrev_b64 v[16:17], 11, v[16:17]
	v_cvt_pk_bf16_f32 v0, v0, s0
	v_lshl_add_u64 v[16:17], v[32:33], 0, v[16:17]
	v_lshlrev_b32_e32 v4, 16, v128
	global_store_short v[16:17], v0, off
	v_fma_f32 v0, v5, v36, v1
	v_mul_f32_e32 v0, v0, v4
	v_cvt_pk_bf16_f32 v0, v0, s0
	global_store_short v[16:17], v0, off offset:64
	v_add_u32_e32 v0, s12, v93
	v_ashrrev_i32_e32 v1, 31, v0
	v_lshlrev_b32_e32 v4, 16, v125
	v_lshlrev_b32_e32 v5, 16, v126
	v_fma_f32 v16, v22, v37, v2
	v_fma_f32 v2, v6, v36, v2
	v_mul_f32_e32 v4, v16, v4
	v_lshlrev_b64 v[0:1], 11, v[0:1]
	v_mul_f32_e32 v2, v2, v5
	v_cvt_pk_bf16_f32 v4, v4, s0
	v_lshl_add_u64 v[0:1], v[32:33], 0, v[0:1]
	v_cvt_pk_bf16_f32 v2, v2, s0
	global_store_short v[0:1], v4, off
	global_store_short v[0:1], v2, off offset:64
	v_add_u32_e32 v0, s12, v94
	v_ashrrev_i32_e32 v1, 31, v0
	v_lshlrev_b32_e32 v2, 16, v123
	v_fma_f32 v5, v23, v37, v3
	v_mul_f32_e32 v2, v5, v2
	v_lshlrev_b64 v[0:1], 11, v[0:1]
	v_lshlrev_b32_e32 v4, 16, v124
	v_cvt_pk_bf16_f32 v2, v2, s0
	v_lshl_add_u64 v[0:1], v[32:33], 0, v[0:1]
	v_fmac_f32_e32 v3, v7, v36
	global_store_short v[0:1], v2, off
	v_mul_f32_e32 v2, v3, v4
	v_cvt_pk_bf16_f32 v2, v2, s0
	global_store_short v[0:1], v2, off offset:64
	v_mov_b32_e32 v0, v52
	v_mov_b32_e32 v1, v53
	v_mov_b32_e32 v2, v54
	v_mov_b32_e32 v3, v55
	v_add_u32_e32 v4, s12, v95
	v_ashrrev_i32_e32 v5, 31, v4
	v_lshlrev_b32_e32 v6, 16, v121
	v_lshlrev_b32_e32 v7, 16, v122
	v_lshlrev_b64 v[4:5], 11, v[4:5]
	v_lshl_add_u64 v[4:5], v[32:33], 0, v[4:5]
	s_nop 0
	v_fma_f32 v16, v24, v37, v0
	v_fma_f32 v0, v8, v36, v0
	v_mul_f32_e32 v6, v16, v6
	v_mul_f32_e32 v0, v0, v7
	v_cvt_pk_bf16_f32 v6, v6, s0
	v_cvt_pk_bf16_f32 v0, v0, s0
	global_store_short v[4:5], v6, off
	global_store_short v[4:5], v0, off offset:64
	v_add_u32_e32 v4, s12, v96
	v_ashrrev_i32_e32 v5, 31, v4
	v_lshlrev_b32_e32 v0, 16, v119
	v_fma_f32 v7, v25, v37, v1
	v_mul_f32_e32 v0, v7, v0
	v_lshlrev_b64 v[4:5], 11, v[4:5]
	v_cvt_pk_bf16_f32 v0, v0, s0
	v_lshl_add_u64 v[4:5], v[32:33], 0, v[4:5]
	v_lshlrev_b32_e32 v6, 16, v120
	global_store_short v[4:5], v0, off
	v_fma_f32 v0, v9, v36, v1
	v_mul_f32_e32 v0, v0, v6
	v_cvt_pk_bf16_f32 v0, v0, s0
	global_store_short v[4:5], v0, off offset:64
	v_add_u32_e32 v0, s12, v97
	v_ashrrev_i32_e32 v1, 31, v0
	v_lshlrev_b32_e32 v4, 16, v117
	v_lshlrev_b32_e32 v5, 16, v118
	v_fma_f32 v6, v26, v37, v2
	v_fma_f32 v2, v10, v36, v2
	v_mul_f32_e32 v4, v6, v4
	v_lshlrev_b64 v[0:1], 11, v[0:1]
	v_mul_f32_e32 v2, v2, v5
	v_cvt_pk_bf16_f32 v4, v4, s0
	v_lshl_add_u64 v[0:1], v[32:33], 0, v[0:1]
	v_cvt_pk_bf16_f32 v2, v2, s0
	global_store_short v[0:1], v4, off
	global_store_short v[0:1], v2, off offset:64
	v_add_u32_e32 v0, s12, v98
	v_ashrrev_i32_e32 v1, 31, v0
	v_lshlrev_b32_e32 v2, 16, v115
	v_fma_f32 v5, v27, v37, v3
	v_mul_f32_e32 v2, v5, v2
	v_lshlrev_b64 v[0:1], 11, v[0:1]
	v_lshlrev_b32_e32 v4, 16, v116
	v_cvt_pk_bf16_f32 v2, v2, s0
	v_lshl_add_u64 v[0:1], v[32:33], 0, v[0:1]
	v_fmac_f32_e32 v3, v11, v36
	global_store_short v[0:1], v2, off
	v_mul_f32_e32 v2, v3, v4
	v_cvt_pk_bf16_f32 v2, v2, s0
	global_store_short v[0:1], v2, off offset:64
	v_mov_b32_e32 v0, v56
	v_mov_b32_e32 v1, v57
	v_mov_b32_e32 v2, v58
	v_mov_b32_e32 v3, v59
	v_add_u32_e32 v4, s12, v99
	v_ashrrev_i32_e32 v5, 31, v4
	v_lshlrev_b32_e32 v6, 16, v113
	v_lshlrev_b32_e32 v7, 16, v114
	v_lshlrev_b64 v[4:5], 11, v[4:5]
	v_lshl_add_u64 v[4:5], v[32:33], 0, v[4:5]
	s_nop 0
	v_fma_f32 v8, v28, v37, v0
	v_fma_f32 v0, v12, v36, v0
	v_mul_f32_e32 v6, v8, v6
	v_mul_f32_e32 v0, v0, v7
	v_cvt_pk_bf16_f32 v6, v6, s0
	v_cvt_pk_bf16_f32 v0, v0, s0
	global_store_short v[4:5], v6, off
	global_store_short v[4:5], v0, off offset:64
	v_add_u32_e32 v4, s12, v100
	v_ashrrev_i32_e32 v5, 31, v4
	v_lshlrev_b32_e32 v0, 16, v111
	v_fma_f32 v7, v29, v37, v1
	v_mul_f32_e32 v0, v7, v0
	v_lshlrev_b64 v[4:5], 11, v[4:5]
	v_cvt_pk_bf16_f32 v0, v0, s0
	v_lshl_add_u64 v[4:5], v[32:33], 0, v[4:5]
	v_lshlrev_b32_e32 v6, 16, v112
	global_store_short v[4:5], v0, off
	v_fma_f32 v0, v13, v36, v1
	v_mul_f32_e32 v0, v0, v6
	v_cvt_pk_bf16_f32 v0, v0, s0
	global_store_short v[4:5], v0, off offset:64
	v_add_u32_e32 v0, s12, v101
	v_ashrrev_i32_e32 v1, 31, v0
	v_lshlrev_b32_e32 v4, 16, v109
	v_lshlrev_b32_e32 v5, 16, v110
	v_fma_f32 v6, v30, v37, v2
	v_fma_f32 v2, v14, v36, v2
	v_mul_f32_e32 v4, v6, v4
	v_lshlrev_b64 v[0:1], 11, v[0:1]
	v_mul_f32_e32 v2, v2, v5
	v_cvt_pk_bf16_f32 v4, v4, s0
	v_lshl_add_u64 v[0:1], v[32:33], 0, v[0:1]
	v_cvt_pk_bf16_f32 v2, v2, s0
	global_store_short v[0:1], v4, off
	global_store_short v[0:1], v2, off offset:64
	v_add_u32_e32 v0, s12, v102
	v_ashrrev_i32_e32 v1, 31, v0
	v_lshlrev_b32_e32 v2, 16, v107
	v_fma_f32 v5, v31, v37, v3
	v_mul_f32_e32 v2, v5, v2
	v_lshlrev_b64 v[0:1], 11, v[0:1]
	v_lshlrev_b32_e32 v4, 16, v108
	v_cvt_pk_bf16_f32 v2, v2, s0
	v_lshl_add_u64 v[0:1], v[32:33], 0, v[0:1]
	v_fmac_f32_e32 v3, v15, v36
	global_store_short v[0:1], v2, off
	v_mul_f32_e32 v2, v3, v4
	v_cvt_pk_bf16_f32 v2, v2, s0
	global_store_short v[0:1], v2, off offset:64
	s_barrier
	s_cbranch_scc0 .LBB0_218
.LBB0_216:
	s_and_b32 s12, s10, 0xffffff80
	s_and_b32 s13, s8, 0x380
	s_lshl_b32 s96, s13, 1
	v_lshl_add_u64 v[4:5], v[60:61], 0, s[96:97]
	v_add_u32_e32 v0, s12, v75
	v_ashrrev_i32_e32 v1, 31, v0
	v_lshlrev_b64 v[0:1], 11, v[0:1]
	v_lshl_add_u64 v[0:1], v[4:5], 0, v[0:1]
	global_load_dwordx4 v[180:183], v[0:1], off nt
	v_add_u32_e32 v0, s12, v76
	v_ashrrev_i32_e32 v1, 31, v0
	v_lshlrev_b64 v[0:1], 11, v[0:1]
	v_lshl_add_u64 v[0:1], v[4:5], 0, v[0:1]
	global_load_dwordx4 v[184:187], v[0:1], off nt
	v_add_u32_e32 v0, s12, v77
	v_ashrrev_i32_e32 v1, 31, v0
	v_lshlrev_b64 v[0:1], 11, v[0:1]
	v_lshl_add_u64 v[0:1], v[4:5], 0, v[0:1]
	global_load_dwordx4 v[188:191], v[0:1], off nt
	v_add_u32_e32 v0, s12, v78
	v_ashrrev_i32_e32 v1, 31, v0
	v_lshlrev_b64 v[0:1], 11, v[0:1]
	v_lshl_add_u64 v[0:1], v[4:5], 0, v[0:1]
	global_load_dwordx4 v[192:195], v[0:1], off nt
	s_and_saveexec_b64 s[2:3], vcc
	s_cbranch_execz .Lsp_norss
	v_add_u32_e32 v0, s12, v70
	v_ashrrev_i32_e32 v1, 31, v0
	v_lshl_add_u64 v[0:1], v[0:1], 2, s[4:5]
	global_load_dword v196, v[0:1], off
.Lsp_norss:
	s_or_b64 exec, exec, s[2:3]
	v_readlane_b32 s98, v254, 29
	v_readlane_b32 s99, v254, 30
	s_nop 0
	v_mov_b32_e32 v216, s98
	v_mov_b32_e32 v217, s99
	ds_read_b64 v[218:219], v216
	ds_read_b64 v[220:221], v217
	v_or_b32_e32 v199, s13, v74
	v_lshlrev_b32_e32 v199, 2, v199
	v_add_u32_e32 v222, s13, v73
	v_ashrrev_i32_e32 v223, 31, v222
	s_waitcnt lgkmcnt(0)
	v_readfirstlane_b32 s98, v218
	v_readfirstlane_b32 s99, v219
	v_lshl_add_u64 v[220:221], v[222:223], 2, v[220:221]
	s_nop 3
	global_load_dword v197, v199, s[98:99]
	global_load_dword v198, v199, s[98:99] offset:128
	global_load_dwordx4 v[200:203], v[220:221], off
	global_load_dwordx4 v[204:207], v[220:221], off offset:32
	global_load_dwordx4 v[208:211], v[220:221], off offset:64
	global_load_dwordx4 v[212:215], v[220:221], off offset:96
	s_branch .LBB0_215
